# GEMM1 trip body duplicated: steady-state copy without PEEL/deferred-store checks (trip 0 keeps them), next-tile prefetch stage moved to loop exit
# speedup vs baseline: 1.0100x; 1.0036x over previous
;   DI bool next(int i, GUnit& u) const { if (i != 0) return false; u.A = A; u.B = B; u.pm = pm; u.pn = pn; u.seg = 8; u.bmode = 1; return true; }
; template <bool PEEL, class Sched, class Epi>
; DI void gemm_stream(LAS unsigned char* lds, int K, long lda, long ldb, const Sched& S, const Epi& E) {
;     ...
;   for (;;) {
;     const bool has_next = S.next(ui + 1, nxt);
;     const char* nA = has_next ? nxt.A : cA; const char* nB = has_next ? nxt.B : cB;
.LBB0_252:
	s_and_b64 s[48:49], s[6:7], exec
	s_cselect_b32 s29, s35, s45
	s_cselect_b32 s43, s34, s44
	s_cselect_b32 s89, s41, s47
	s_cselect_b32 s90, s40, s46
	s_cmp_eq_u32 s87, 2
	s_cselect_b32 s4, s52, 0x20000
	s_cselect_b32 s48, s53, 0x40000
	s_add_u32 s44, s44, 0x40080
	s_addc_u32 s45, s45, 0
	s_add_u32 s91, s46, 0x100
	s_mov_b32 s49, s5
	s_addc_u32 s92, s47, 0
	s_mov_b32 s93, -2
	s_mov_b64 s[46:47], 0
	s_branch .LBB0_254
.LBB0_253:
	v_lshlrev_b32_e32 v132, 6, v132
	v_sub_u32_e32 v131, v131, v132
	v_lshlrev_b32_e32 v130, 5, v130
	v_ashrrev_i16_sdwa v131, v151, sext(v131) dst_sel:DWORD dst_unused:UNUSED_PAD src0_sel:DWORD src1_sel:BYTE_0
	v_and_b32_e32 v130, 32, v130
	v_bfe_i32 v131, v131, 0, 16
	v_add_lshl_u32 v130, v130, v131, 1
	v_lshl_add_u32 v148, v134, 11, v130
	s_mov_b64 s[30:31], s[4:5]
	s_mov_b64 s[18:19], s[48:49]
	s_branch .Lgb_body

.Lpl_wdone:
	s_barrier
	v_mfma_f32_16x16x32_f16 v[90:93], v[202:205], v[170:173], v[90:93]
	v_mfma_f32_16x16x32_f16 v[94:97], v[210:213], v[170:173], v[94:97]
	v_mfma_f32_16x16x32_f16 v[82:85], v[202:205], v[178:181], v[82:85]
	v_mfma_f32_16x16x32_f16 v[86:89], v[210:213], v[178:181], v[86:89]
	v_mfma_f32_16x16x32_f16 v[74:77], v[202:205], v[186:189], v[74:77]
	v_mfma_f32_16x16x32_f16 v[78:81], v[210:213], v[186:189], v[78:81]
	v_mfma_f32_16x16x32_f16 v[70:73], v[202:205], v[194:197], v[70:73]
	v_mfma_f32_16x16x32_f16 v[66:69], v[210:213], v[194:197], v[66:69]
	v_mfma_f32_16x16x32_f16 v[90:93], v[206:209], v[174:177], v[90:93]
	v_mfma_f32_16x16x32_f16 v[94:97], v[214:217], v[174:177], v[94:97]
	v_mfma_f32_16x16x32_f16 v[82:85], v[206:209], v[182:185], v[82:85]
	v_mfma_f32_16x16x32_f16 v[86:89], v[214:217], v[182:185], v[86:89]
	v_mfma_f32_16x16x32_f16 v[74:77], v[206:209], v[190:193], v[74:77]
	v_mfma_f32_16x16x32_f16 v[78:81], v[214:217], v[190:193], v[78:81]
	v_mfma_f32_16x16x32_f16 v[70:73], v[206:209], v[198:201], v[70:73]
	v_mfma_f32_16x16x32_f16 v[66:69], v[214:217], v[198:201], v[66:69]
	s_barrier
	ds_read_b128 v[130:133], v254 offset:32768
	ds_read_b128 v[134:137], v254 offset:33792
	ds_read_b128 v[138:141], v254 offset:34816
	ds_read_b128 v[142:145], v254 offset:35840
	s_mov_b32 m0, s61
	v_lshl_add_u64 v[202:203], v[218:219], 0, s[8:9]
	ds_read_b128 v[170:173], v165 offset:32768
	ds_read_b128 v[174:177], v165 offset:33792
	ds_read_b128 v[178:181], v165 offset:34816
	ds_read_b128 v[182:185], v165 offset:35840
	ds_read_b128 v[186:189], v165 offset:36864
	ds_read_b128 v[190:193], v165 offset:37888
	ds_read_b128 v[194:197], v165 offset:38912
	ds_read_b128 v[198:201], v165 offset:39936
	global_load_lds_dwordx4 v[202:203], off
	v_lshl_add_u64 v[202:203], v[218:219], 0, s[12:13]
	s_mov_b32 m0, s62
	s_nop 0
	global_load_lds_dwordx4 v[202:203], off
	s_waitcnt lgkmcnt(8)
	s_barrier
	s_waitcnt lgkmcnt(0)
	s_waitcnt lgkmcnt(0)
	v_mfma_f32_16x16x32_f16 v[58:61], v[130:133], v[170:173], v[58:61]
	v_mfma_f32_16x16x32_f16 v[62:65], v[138:141], v[170:173], v[62:65]
	v_mfma_f32_16x16x32_f16 v[50:53], v[130:133], v[178:181], v[50:53]
	v_mfma_f32_16x16x32_f16 v[54:57], v[138:141], v[178:181], v[54:57]
	v_mfma_f32_16x16x32_f16 v[42:45], v[130:133], v[186:189], v[42:45]
	v_mfma_f32_16x16x32_f16 v[46:49], v[138:141], v[186:189], v[46:49]
	v_mfma_f32_16x16x32_f16 v[26:29], v[130:133], v[194:197], v[26:29]
	v_mfma_f32_16x16x32_f16 v[30:33], v[138:141], v[194:197], v[30:33]
	v_mfma_f32_16x16x32_f16 v[58:61], v[134:137], v[174:177], v[58:61]
	v_mfma_f32_16x16x32_f16 v[62:65], v[142:145], v[174:177], v[62:65]
	v_mfma_f32_16x16x32_f16 v[50:53], v[134:137], v[182:185], v[50:53]
	v_mfma_f32_16x16x32_f16 v[54:57], v[142:145], v[182:185], v[54:57]
	v_mfma_f32_16x16x32_f16 v[42:45], v[134:137], v[190:193], v[42:45]
	v_mfma_f32_16x16x32_f16 v[46:49], v[142:145], v[190:193], v[46:49]
	v_mfma_f32_16x16x32_f16 v[26:29], v[134:137], v[198:201], v[26:29]
	v_mfma_f32_16x16x32_f16 v[30:33], v[142:145], v[198:201], v[30:33]
	s_barrier
	s_mov_b32 m0, s63
	ds_read_b128 v[202:205], v254 offset:49152
	ds_read_b128 v[206:209], v254 offset:50176
	v_lshl_add_u64 v[162:163], v[162:163], 0, s[14:15]
	ds_read_b128 v[210:213], v254 offset:51200
	ds_read_b128 v[214:217], v254 offset:52224
	global_load_lds_dwordx4 v[162:163], off
	v_lshl_add_u64 v[162:163], v[166:167], 0, s[14:15]
	s_mov_b32 m0, s64
	s_nop 0
	global_load_lds_dwordx4 v[162:163], off
	s_barrier
; template <bool PEEL, class Sched, class Epi>
; DI void gemm_stream(LAS unsigned char* lds, int K, long lda, long ldb, const Sched& S, const Epi& E) {
;     ...
;     if (PEEL) { GS_TRIP(0, 1); for (int t = 2; t < nt; t += 2) { GS_TRIP(t, 0); } }
;     else { for (int t = 0; t < nt; t += 2) { GS_TRIP(t, 0); } }
	s_waitcnt lgkmcnt(0)
	s_waitcnt lgkmcnt(0)
	v_mfma_f32_16x16x32_f16 v[122:125], v[202:205], v[170:173], v[122:125]
	v_mfma_f32_16x16x32_f16 v[126:129], v[210:213], v[170:173], v[126:129]
	v_mfma_f32_16x16x32_f16 v[114:117], v[202:205], v[178:181], v[114:117]
	v_mfma_f32_16x16x32_f16 v[118:121], v[210:213], v[178:181], v[118:121]
	v_mfma_f32_16x16x32_f16 v[106:109], v[202:205], v[186:189], v[106:109]
	v_mfma_f32_16x16x32_f16 v[110:113], v[210:213], v[186:189], v[110:113]
	v_mfma_f32_16x16x32_f16 v[98:101], v[202:205], v[194:197], v[98:101]
	v_mfma_f32_16x16x32_f16 v[102:105], v[210:213], v[194:197], v[102:105]
	v_mfma_f32_16x16x32_f16 v[122:125], v[206:209], v[174:177], v[122:125]
	v_mfma_f32_16x16x32_f16 v[126:129], v[214:217], v[174:177], v[126:129]
	v_mfma_f32_16x16x32_f16 v[114:117], v[206:209], v[182:185], v[114:117]
	v_mfma_f32_16x16x32_f16 v[118:121], v[214:217], v[182:185], v[118:121]
	v_mfma_f32_16x16x32_f16 v[106:109], v[206:209], v[190:193], v[106:109]
	v_mfma_f32_16x16x32_f16 v[110:113], v[214:217], v[190:193], v[110:113]
	v_mfma_f32_16x16x32_f16 v[98:101], v[206:209], v[198:201], v[98:101]
	v_mfma_f32_16x16x32_f16 v[102:105], v[214:217], v[198:201], v[102:105]
	s_mov_b32 m0, s65
	v_lshl_add_u64 v[162:163], v[218:219], 0, s[14:15]
	s_barrier
	ds_read_b128 v[170:173], v165 offset:49152
	ds_read_b128 v[174:177], v165 offset:50176
	ds_read_b128 v[178:181], v165 offset:51200
	ds_read_b128 v[182:185], v165 offset:52224
	ds_read_b128 v[186:189], v165 offset:53248
	ds_read_b128 v[190:193], v165 offset:54272
	ds_read_b128 v[194:197], v165 offset:55296
	ds_read_b128 v[198:201], v165 offset:56320
	global_load_lds_dwordx4 v[162:163], off
	v_lshl_add_u64 v[162:163], v[218:219], 0, s[16:17]
	s_mov_b32 m0, s72
	s_nop 0
	global_load_lds_dwordx4 v[162:163], off
	s_barrier
	s_waitcnt lgkmcnt(0)
	s_waitcnt lgkmcnt(0)
	v_mfma_f32_16x16x32_f16 v[34:37], v[130:133], v[170:173], v[34:37]
	v_mfma_f32_16x16x32_f16 v[38:41], v[138:141], v[170:173], v[38:41]
	v_mfma_f32_16x16x32_f16 v[18:21], v[130:133], v[178:181], v[18:21]
	v_mfma_f32_16x16x32_f16 v[22:25], v[138:141], v[178:181], v[22:25]
	v_mfma_f32_16x16x32_f16 v[10:13], v[130:133], v[186:189], v[10:13]
	v_mfma_f32_16x16x32_f16 v[14:17], v[138:141], v[186:189], v[14:17]
	v_mfma_f32_16x16x32_f16 v[2:5], v[130:133], v[194:197], v[2:5]
	v_mfma_f32_16x16x32_f16 v[6:9], v[138:141], v[194:197], v[6:9]
	v_mfma_f32_16x16x32_f16 v[34:37], v[134:137], v[174:177], v[34:37]
	v_mfma_f32_16x16x32_f16 v[38:41], v[142:145], v[174:177], v[38:41]
	v_mfma_f32_16x16x32_f16 v[18:21], v[134:137], v[182:185], v[18:21]
	v_mfma_f32_16x16x32_f16 v[22:25], v[142:145], v[182:185], v[22:25]
	v_mfma_f32_16x16x32_f16 v[10:13], v[134:137], v[190:193], v[10:13]
	v_mfma_f32_16x16x32_f16 v[14:17], v[142:145], v[190:193], v[14:17]
	v_mfma_f32_16x16x32_f16 v[2:5], v[134:137], v[198:201], v[2:5]
	v_mfma_f32_16x16x32_f16 v[6:9], v[142:145], v[198:201], v[6:9]
	s_barrier
	s_mov_b32 m0, s73
	v_lshl_add_u64 v[130:131], v[220:221], 0, s[14:15]
	global_load_lds_dwordx4 v[130:131], off
	v_lshl_add_u64 v[130:131], v[222:223], 0, s[14:15]
	s_mov_b32 m0, s74
	s_nop 0
	global_load_lds_dwordx4 v[130:131], off
	s_waitcnt vmcnt(6)
	s_barrier
	v_mfma_f32_16x16x32_f16 v[90:93], v[202:205], v[170:173], v[90:93]
	v_mfma_f32_16x16x32_f16 v[94:97], v[210:213], v[170:173], v[94:97]
	v_mfma_f32_16x16x32_f16 v[82:85], v[202:205], v[178:181], v[82:85]
	v_mfma_f32_16x16x32_f16 v[86:89], v[210:213], v[178:181], v[86:89]
	v_mfma_f32_16x16x32_f16 v[74:77], v[202:205], v[186:189], v[74:77]
	v_mfma_f32_16x16x32_f16 v[78:81], v[210:213], v[186:189], v[78:81]
	v_mfma_f32_16x16x32_f16 v[70:73], v[202:205], v[194:197], v[70:73]
	v_mfma_f32_16x16x32_f16 v[66:69], v[210:213], v[194:197], v[66:69]
	v_mfma_f32_16x16x32_f16 v[90:93], v[206:209], v[174:177], v[90:93]
	v_mfma_f32_16x16x32_f16 v[94:97], v[214:217], v[174:177], v[94:97]
	v_mfma_f32_16x16x32_f16 v[82:85], v[206:209], v[182:185], v[82:85]
	v_mfma_f32_16x16x32_f16 v[86:89], v[214:217], v[182:185], v[86:89]
	v_mfma_f32_16x16x32_f16 v[74:77], v[206:209], v[190:193], v[74:77]
	v_mfma_f32_16x16x32_f16 v[78:81], v[214:217], v[190:193], v[78:81]
	v_mfma_f32_16x16x32_f16 v[70:73], v[206:209], v[198:201], v[70:73]
	v_mfma_f32_16x16x32_f16 v[66:69], v[214:217], v[198:201], v[66:69]
	s_add_i32 s93, s93, 2
	s_add_u32 s44, s44, 0x100
	s_addc_u32 s45, s45, 0
	s_add_u32 s91, s91, 0x100
	s_addc_u32 s92, s92, 0
	s_cmp_gt_u32 s93, 13
	s_barrier
	s_cbranch_scc1 .LBB0_264

; DI int brow_of(int bmode, int h, int R) {
;   return bmode == 0 ? 128 * h + R : (bmode == 1 ? 128 * h + (R & ~31) + perm32(R & 31) : 64 * (R >> 5) + 32 * h + perm32(R & 31));
; }
.Lgb_hdr_rest:
	v_mov_b32_e32 v131, v0
	s_cmp_lt_i32 s87, 1
	v_ashrrev_i32_e32 v130, 31, v131
	v_lshrrev_b32_e32 v130, 26, v130
	v_lshlrev_b32_e32 v132, 4, v131
	v_add_u32_e32 v130, v131, v130
	v_bfe_i32 v131, v131, 27, 1
	v_lshrrev_b32_e32 v131, 22, v131
	v_add_u32_e32 v131, v132, v131
	v_and_b32_e32 v131, 0xfffffc00, v131
	v_sub_u32_e32 v131, v132, v131
	v_ashrrev_i32_e32 v130, 6, v130
	v_lshrrev_b32_e32 v132, 4, v131
	v_bitop3_b32 v131, v132, v131, 32 bitop3:0x6c
	v_lshlrev_b32_e32 v132, 3, v130
	v_and_b32_e32 v133, -16, v132
	v_ashrrev_i32_e32 v132, 31, v131
	v_lshrrev_b32_e32 v132, 26, v132
	v_add_u32_e32 v132, v131, v132
	v_ashrrev_i32_e32 v132, 6, v132
	v_add_u32_e32 v133, v132, v133
	s_cbranch_scc1 .LBB0_260
	s_cmp_eq_u32 s87, 1
	s_mov_b64 s[18:19], -1
	s_cbranch_scc0 .LBB0_259
	v_lshlrev_b32_e32 v134, 1, v133
	v_lshrrev_b32_e32 v135, 2, v133
	v_and_b32_e32 v134, 24, v134
	v_and_b32_e32 v135, 4, v135
	v_and_b32_e32 v136, 0xffffffe3, v133
	v_or3_b32 v134, v135, v136, v134
	s_mov_b64 s[18:19], 0

.Lgb_body:
	ds_read_b128 v[130:133], v254
	ds_read_b128 v[134:137], v254 offset:1024
	ds_read_b128 v[138:141], v254 offset:2048
	ds_read_b128 v[142:145], v254 offset:3072
	s_add_u32 s94, s44, 0xfffc0080
	s_addc_u32 s95, s45, -1
	s_and_b64 s[46:47], s[46:47], exec
	s_cselect_b32 s95, s29, s95
	s_cselect_b32 s94, s43, s94
	s_cselect_b32 s47, s89, s92
	s_cselect_b32 s46, s90, s91
	s_mov_b32 m0, s79
	v_lshl_add_u64 v[162:163], s[44:45], 0, v[160:161]
	ds_read_b128 v[170:173], v165
	ds_read_b128 v[174:177], v165 offset:1024
	ds_read_b128 v[178:181], v165 offset:2048
	ds_read_b128 v[182:185], v165 offset:3072
	ds_read_b128 v[186:189], v165 offset:4096
	ds_read_b128 v[190:193], v165 offset:5120
	ds_read_b128 v[194:197], v165 offset:6144
	ds_read_b128 v[198:201], v165 offset:7168
	global_load_lds_dwordx4 v[162:163], off
	v_lshl_add_u64 v[162:163], v[162:163], 0, s[0:1]
	s_mov_b32 m0, s80
	s_nop 0
	global_load_lds_dwordx4 v[162:163], off
	s_waitcnt lgkmcnt(8)
	s_barrier
	s_waitcnt lgkmcnt(0)
	s_waitcnt lgkmcnt(0)
	v_mfma_f32_16x16x32_f16 v[58:61], v[130:133], v[170:173], v[58:61]
	v_mfma_f32_16x16x32_f16 v[62:65], v[138:141], v[170:173], v[62:65]
	v_mfma_f32_16x16x32_f16 v[50:53], v[130:133], v[178:181], v[50:53]
	v_mfma_f32_16x16x32_f16 v[54:57], v[138:141], v[178:181], v[54:57]
	v_mfma_f32_16x16x32_f16 v[42:45], v[130:133], v[186:189], v[42:45]
	v_mfma_f32_16x16x32_f16 v[46:49], v[138:141], v[186:189], v[46:49]
	v_mfma_f32_16x16x32_f16 v[26:29], v[130:133], v[194:197], v[26:29]
	v_mfma_f32_16x16x32_f16 v[30:33], v[138:141], v[194:197], v[30:33]
	v_mfma_f32_16x16x32_f16 v[58:61], v[134:137], v[174:177], v[58:61]
	v_mfma_f32_16x16x32_f16 v[62:65], v[142:145], v[174:177], v[62:65]
	v_mfma_f32_16x16x32_f16 v[50:53], v[134:137], v[182:185], v[50:53]
	v_mfma_f32_16x16x32_f16 v[54:57], v[142:145], v[182:185], v[54:57]
	v_mfma_f32_16x16x32_f16 v[42:45], v[134:137], v[190:193], v[42:45]
	v_mfma_f32_16x16x32_f16 v[46:49], v[142:145], v[190:193], v[46:49]
	v_mfma_f32_16x16x32_f16 v[26:29], v[134:137], v[198:201], v[26:29]
	v_mfma_f32_16x16x32_f16 v[30:33], v[142:145], v[198:201], v[30:33]
	s_barrier
	s_mov_b32 m0, s54
	ds_read_b128 v[202:205], v254 offset:16384
	ds_read_b128 v[206:209], v254 offset:17408
	s_add_u32 s96, s46, s30
	ds_read_b128 v[210:213], v254 offset:18432
	ds_read_b128 v[214:217], v254 offset:19456
	global_load_lds_dwordx4 v148, s[46:47]
	s_addc_u32 s97, s47, s31
	s_mov_b32 m0, s55
	v_lshl_add_u64 v[162:163], s[46:47], 0, v[148:149]
	global_load_lds_dwordx4 v148, s[96:97]
	s_barrier
	s_waitcnt lgkmcnt(0)
	v_lshl_add_u64 v[166:167], s[96:97], 0, v[148:149]
	s_waitcnt lgkmcnt(0)
	v_mfma_f32_16x16x32_f16 v[122:125], v[202:205], v[170:173], v[122:125]
	v_mfma_f32_16x16x32_f16 v[126:129], v[210:213], v[170:173], v[126:129]
	v_mfma_f32_16x16x32_f16 v[114:117], v[202:205], v[178:181], v[114:117]
	v_mfma_f32_16x16x32_f16 v[118:121], v[210:213], v[178:181], v[118:121]
	v_mfma_f32_16x16x32_f16 v[106:109], v[202:205], v[186:189], v[106:109]
	v_mfma_f32_16x16x32_f16 v[110:113], v[210:213], v[186:189], v[110:113]
	v_mfma_f32_16x16x32_f16 v[98:101], v[202:205], v[194:197], v[98:101]
	v_mfma_f32_16x16x32_f16 v[102:105], v[210:213], v[194:197], v[102:105]
	v_mfma_f32_16x16x32_f16 v[122:125], v[206:209], v[174:177], v[122:125]
	v_mfma_f32_16x16x32_f16 v[126:129], v[214:217], v[174:177], v[126:129]
	v_mfma_f32_16x16x32_f16 v[114:117], v[206:209], v[182:185], v[114:117]
	v_mfma_f32_16x16x32_f16 v[118:121], v[214:217], v[182:185], v[118:121]
	v_mfma_f32_16x16x32_f16 v[106:109], v[206:209], v[190:193], v[106:109]
	v_mfma_f32_16x16x32_f16 v[110:113], v[214:217], v[190:193], v[110:113]
	v_mfma_f32_16x16x32_f16 v[98:101], v[206:209], v[198:201], v[98:101]
	v_mfma_f32_16x16x32_f16 v[102:105], v[214:217], v[198:201], v[102:105]
	s_mov_b32 m0, s51
	v_lshl_add_u64 v[218:219], s[94:95], 0, v[146:147]
	s_barrier
	ds_read_b128 v[170:173], v165 offset:16384
	ds_read_b128 v[174:177], v165 offset:17408
	ds_read_b128 v[178:181], v165 offset:18432
	ds_read_b128 v[182:185], v165 offset:19456
	ds_read_b128 v[186:189], v165 offset:20480
	ds_read_b128 v[190:193], v165 offset:21504
	ds_read_b128 v[194:197], v165 offset:22528
	ds_read_b128 v[198:201], v165 offset:23552
	global_load_lds_dwordx4 v[218:219], off
	v_lshl_add_u64 v[220:221], v[218:219], 0, s[0:1]
	s_mov_b32 m0, s56
	s_nop 0
	global_load_lds_dwordx4 v[220:221], off
	s_barrier
	s_waitcnt lgkmcnt(0)
	s_waitcnt lgkmcnt(0)
	v_mfma_f32_16x16x32_f16 v[34:37], v[130:133], v[170:173], v[34:37]
	v_mfma_f32_16x16x32_f16 v[38:41], v[138:141], v[170:173], v[38:41]
	v_mfma_f32_16x16x32_f16 v[18:21], v[130:133], v[178:181], v[18:21]
	v_mfma_f32_16x16x32_f16 v[22:25], v[138:141], v[178:181], v[22:25]
	v_mfma_f32_16x16x32_f16 v[10:13], v[130:133], v[186:189], v[10:13]
	v_mfma_f32_16x16x32_f16 v[14:17], v[138:141], v[186:189], v[14:17]
	v_mfma_f32_16x16x32_f16 v[2:5], v[130:133], v[194:197], v[2:5]
	v_mfma_f32_16x16x32_f16 v[6:9], v[138:141], v[194:197], v[6:9]
	v_mfma_f32_16x16x32_f16 v[34:37], v[134:137], v[174:177], v[34:37]
	v_mfma_f32_16x16x32_f16 v[38:41], v[142:145], v[174:177], v[38:41]
	v_mfma_f32_16x16x32_f16 v[18:21], v[134:137], v[182:185], v[18:21]
	v_mfma_f32_16x16x32_f16 v[22:25], v[142:145], v[182:185], v[22:25]
	v_mfma_f32_16x16x32_f16 v[10:13], v[134:137], v[190:193], v[10:13]
	v_mfma_f32_16x16x32_f16 v[14:17], v[142:145], v[190:193], v[14:17]
	v_mfma_f32_16x16x32_f16 v[2:5], v[134:137], v[198:201], v[2:5]
	v_mfma_f32_16x16x32_f16 v[6:9], v[142:145], v[198:201], v[6:9]
	s_barrier
	s_add_u32 s46, s46, s18
	s_addc_u32 s47, s47, s19
	s_mov_b32 m0, s57
	v_lshl_add_u64 v[220:221], s[46:47], 0, v[148:149]
	global_load_lds_dwordx4 v148, s[46:47]
	s_add_u32 s46, s46, s30
	s_addc_u32 s47, s47, s31
	s_mov_b32 m0, s60
	v_lshl_add_u64 v[222:223], s[46:47], 0, v[148:149]
	global_load_lds_dwordx4 v148, s[46:47]
	s_waitcnt vmcnt(6)
	s_barrier
	v_mfma_f32_16x16x32_f16 v[90:93], v[202:205], v[170:173], v[90:93]
	v_mfma_f32_16x16x32_f16 v[94:97], v[210:213], v[170:173], v[94:97]
	v_mfma_f32_16x16x32_f16 v[82:85], v[202:205], v[178:181], v[82:85]
	v_mfma_f32_16x16x32_f16 v[86:89], v[210:213], v[178:181], v[86:89]
	v_mfma_f32_16x16x32_f16 v[74:77], v[202:205], v[186:189], v[74:77]
	v_mfma_f32_16x16x32_f16 v[78:81], v[210:213], v[186:189], v[78:81]
	v_mfma_f32_16x16x32_f16 v[70:73], v[202:205], v[194:197], v[70:73]
	v_mfma_f32_16x16x32_f16 v[66:69], v[210:213], v[194:197], v[66:69]
	v_mfma_f32_16x16x32_f16 v[90:93], v[206:209], v[174:177], v[90:93]
	v_mfma_f32_16x16x32_f16 v[94:97], v[214:217], v[174:177], v[94:97]
	v_mfma_f32_16x16x32_f16 v[82:85], v[206:209], v[182:185], v[82:85]
	v_mfma_f32_16x16x32_f16 v[86:89], v[214:217], v[182:185], v[86:89]
	v_mfma_f32_16x16x32_f16 v[74:77], v[206:209], v[190:193], v[74:77]
	v_mfma_f32_16x16x32_f16 v[78:81], v[214:217], v[190:193], v[78:81]
	v_mfma_f32_16x16x32_f16 v[70:73], v[206:209], v[198:201], v[70:73]
	v_mfma_f32_16x16x32_f16 v[66:69], v[214:217], v[198:201], v[66:69]
	s_barrier
	ds_read_b128 v[130:133], v254 offset:32768
	ds_read_b128 v[134:137], v254 offset:33792
	ds_read_b128 v[138:141], v254 offset:34816
	ds_read_b128 v[142:145], v254 offset:35840
	s_mov_b32 m0, s61
	v_lshl_add_u64 v[202:203], v[218:219], 0, s[8:9]
	ds_read_b128 v[170:173], v165 offset:32768
	ds_read_b128 v[174:177], v165 offset:33792
	ds_read_b128 v[178:181], v165 offset:34816
	ds_read_b128 v[182:185], v165 offset:35840
	ds_read_b128 v[186:189], v165 offset:36864
	ds_read_b128 v[190:193], v165 offset:37888
	ds_read_b128 v[194:197], v165 offset:38912
	ds_read_b128 v[198:201], v165 offset:39936
	global_load_lds_dwordx4 v[202:203], off
	v_lshl_add_u64 v[202:203], v[218:219], 0, s[12:13]
	s_mov_b32 m0, s62
	s_nop 0
	global_load_lds_dwordx4 v[202:203], off
	s_waitcnt lgkmcnt(8)
	s_barrier
	s_waitcnt lgkmcnt(0)
	s_waitcnt lgkmcnt(0)
	v_mfma_f32_16x16x32_f16 v[58:61], v[130:133], v[170:173], v[58:61]
	v_mfma_f32_16x16x32_f16 v[62:65], v[138:141], v[170:173], v[62:65]
	v_mfma_f32_16x16x32_f16 v[50:53], v[130:133], v[178:181], v[50:53]
	v_mfma_f32_16x16x32_f16 v[54:57], v[138:141], v[178:181], v[54:57]
	v_mfma_f32_16x16x32_f16 v[42:45], v[130:133], v[186:189], v[42:45]
	v_mfma_f32_16x16x32_f16 v[46:49], v[138:141], v[186:189], v[46:49]
	v_mfma_f32_16x16x32_f16 v[26:29], v[130:133], v[194:197], v[26:29]
	v_mfma_f32_16x16x32_f16 v[30:33], v[138:141], v[194:197], v[30:33]
	v_mfma_f32_16x16x32_f16 v[58:61], v[134:137], v[174:177], v[58:61]
	v_mfma_f32_16x16x32_f16 v[62:65], v[142:145], v[174:177], v[62:65]
	v_mfma_f32_16x16x32_f16 v[50:53], v[134:137], v[182:185], v[50:53]
	v_mfma_f32_16x16x32_f16 v[54:57], v[142:145], v[182:185], v[54:57]
	v_mfma_f32_16x16x32_f16 v[42:45], v[134:137], v[190:193], v[42:45]
	v_mfma_f32_16x16x32_f16 v[46:49], v[142:145], v[190:193], v[46:49]
	v_mfma_f32_16x16x32_f16 v[26:29], v[134:137], v[198:201], v[26:29]
	v_mfma_f32_16x16x32_f16 v[30:33], v[142:145], v[198:201], v[30:33]
	s_barrier
	s_mov_b32 m0, s63
	ds_read_b128 v[202:205], v254 offset:49152
	ds_read_b128 v[206:209], v254 offset:50176
	v_lshl_add_u64 v[162:163], v[162:163], 0, s[14:15]
	ds_read_b128 v[210:213], v254 offset:51200
	ds_read_b128 v[214:217], v254 offset:52224
	global_load_lds_dwordx4 v[162:163], off
	v_lshl_add_u64 v[162:163], v[166:167], 0, s[14:15]
	s_mov_b32 m0, s64
	s_nop 0
	global_load_lds_dwordx4 v[162:163], off
	s_barrier
; #define GS_STAGE(bufoff, gbase, voff, step) do { \
;     __builtin_amdgcn_global_load_lds((const unsigned*)((const char*)(gbase) + (voff)), (LAS unsigned*)(lds + (bufoff) + ldsw), 16, 0, 0); \
;     __builtin_amdgcn_global_load_lds((const unsigned*)((const char*)(gbase) + (step) + (voff)), (LAS unsigned*)(lds + (bufoff) + ldsw + 8192), 16, 0, 0); } while (0)
; #define GS_WAIT_V(n) asm volatile("s_waitcnt vmcnt(" #n ")" ::: "memory")
; template <bool PEEL, class Sched, class Epi>
; DI void gemm_stream(LAS unsigned char* lds, int K, long lda, long ldb, const Sched& S, const Epi& E) {
;     ...
;     if (PEEL) { GS_TRIP(0, 1); for (int t = 2; t < nt; t += 2) { GS_TRIP(t, 0); } }
;     else { for (int t = 0; t < nt; t += 2) { GS_TRIP(t, 0); } }
;     ...
;     if (PEEL && has_next) {
;       GS_STAGE(GS_SA(1, 1), nA + kstep + hstepA, voffA, stepA);
;       GS_WAIT_V(0);
;     }
	s_waitcnt lgkmcnt(0)
	s_waitcnt lgkmcnt(0)
	v_mfma_f32_16x16x32_f16 v[122:125], v[202:205], v[170:173], v[122:125]
	v_mfma_f32_16x16x32_f16 v[126:129], v[210:213], v[170:173], v[126:129]
	v_mfma_f32_16x16x32_f16 v[114:117], v[202:205], v[178:181], v[114:117]
	v_mfma_f32_16x16x32_f16 v[118:121], v[210:213], v[178:181], v[118:121]
	v_mfma_f32_16x16x32_f16 v[106:109], v[202:205], v[186:189], v[106:109]
	v_mfma_f32_16x16x32_f16 v[110:113], v[210:213], v[186:189], v[110:113]
	v_mfma_f32_16x16x32_f16 v[98:101], v[202:205], v[194:197], v[98:101]
	v_mfma_f32_16x16x32_f16 v[102:105], v[210:213], v[194:197], v[102:105]
	v_mfma_f32_16x16x32_f16 v[122:125], v[206:209], v[174:177], v[122:125]
	v_mfma_f32_16x16x32_f16 v[126:129], v[214:217], v[174:177], v[126:129]
	v_mfma_f32_16x16x32_f16 v[114:117], v[206:209], v[182:185], v[114:117]
	v_mfma_f32_16x16x32_f16 v[118:121], v[214:217], v[182:185], v[118:121]
	v_mfma_f32_16x16x32_f16 v[106:109], v[206:209], v[190:193], v[106:109]
	v_mfma_f32_16x16x32_f16 v[110:113], v[214:217], v[190:193], v[110:113]
	v_mfma_f32_16x16x32_f16 v[98:101], v[206:209], v[198:201], v[98:101]
	v_mfma_f32_16x16x32_f16 v[102:105], v[214:217], v[198:201], v[102:105]
	s_mov_b32 m0, s65
	v_lshl_add_u64 v[162:163], v[218:219], 0, s[14:15]
	s_barrier
	ds_read_b128 v[170:173], v165 offset:49152
	ds_read_b128 v[174:177], v165 offset:50176
	ds_read_b128 v[178:181], v165 offset:51200
	ds_read_b128 v[182:185], v165 offset:52224
	ds_read_b128 v[186:189], v165 offset:53248
	ds_read_b128 v[190:193], v165 offset:54272
	ds_read_b128 v[194:197], v165 offset:55296
	ds_read_b128 v[198:201], v165 offset:56320
	global_load_lds_dwordx4 v[162:163], off
	v_lshl_add_u64 v[162:163], v[218:219], 0, s[16:17]
	s_mov_b32 m0, s72
	s_nop 0
	global_load_lds_dwordx4 v[162:163], off
	s_barrier
	s_waitcnt lgkmcnt(0)
	s_waitcnt lgkmcnt(0)
	v_mfma_f32_16x16x32_f16 v[34:37], v[130:133], v[170:173], v[34:37]
	v_mfma_f32_16x16x32_f16 v[38:41], v[138:141], v[170:173], v[38:41]
	v_mfma_f32_16x16x32_f16 v[18:21], v[130:133], v[178:181], v[18:21]
	v_mfma_f32_16x16x32_f16 v[22:25], v[138:141], v[178:181], v[22:25]
	v_mfma_f32_16x16x32_f16 v[10:13], v[130:133], v[186:189], v[10:13]
	v_mfma_f32_16x16x32_f16 v[14:17], v[138:141], v[186:189], v[14:17]
	v_mfma_f32_16x16x32_f16 v[2:5], v[130:133], v[194:197], v[2:5]
	v_mfma_f32_16x16x32_f16 v[6:9], v[138:141], v[194:197], v[6:9]
	v_mfma_f32_16x16x32_f16 v[34:37], v[134:137], v[174:177], v[34:37]
	v_mfma_f32_16x16x32_f16 v[38:41], v[142:145], v[174:177], v[38:41]
	v_mfma_f32_16x16x32_f16 v[18:21], v[134:137], v[182:185], v[18:21]
	v_mfma_f32_16x16x32_f16 v[22:25], v[142:145], v[182:185], v[22:25]
	v_mfma_f32_16x16x32_f16 v[10:13], v[134:137], v[190:193], v[10:13]
	v_mfma_f32_16x16x32_f16 v[14:17], v[142:145], v[190:193], v[14:17]
	v_mfma_f32_16x16x32_f16 v[2:5], v[134:137], v[198:201], v[2:5]
	v_mfma_f32_16x16x32_f16 v[6:9], v[142:145], v[198:201], v[6:9]
	s_barrier
	s_mov_b32 m0, s73
	v_lshl_add_u64 v[130:131], v[220:221], 0, s[14:15]
	global_load_lds_dwordx4 v[130:131], off
	v_lshl_add_u64 v[130:131], v[222:223], 0, s[14:15]
	s_mov_b32 m0, s74
	s_nop 0
	global_load_lds_dwordx4 v[130:131], off
	s_waitcnt vmcnt(6)
	s_barrier
	v_mfma_f32_16x16x32_f16 v[90:93], v[202:205], v[170:173], v[90:93]
	v_mfma_f32_16x16x32_f16 v[94:97], v[210:213], v[170:173], v[94:97]
	v_mfma_f32_16x16x32_f16 v[82:85], v[202:205], v[178:181], v[82:85]
	v_mfma_f32_16x16x32_f16 v[86:89], v[210:213], v[178:181], v[86:89]
	v_mfma_f32_16x16x32_f16 v[74:77], v[202:205], v[186:189], v[74:77]
	v_mfma_f32_16x16x32_f16 v[78:81], v[210:213], v[186:189], v[78:81]
	v_mfma_f32_16x16x32_f16 v[70:73], v[202:205], v[194:197], v[70:73]
	v_mfma_f32_16x16x32_f16 v[66:69], v[210:213], v[194:197], v[66:69]
	v_mfma_f32_16x16x32_f16 v[90:93], v[206:209], v[174:177], v[90:93]
	v_mfma_f32_16x16x32_f16 v[94:97], v[214:217], v[174:177], v[94:97]
	v_mfma_f32_16x16x32_f16 v[82:85], v[206:209], v[182:185], v[82:85]
	v_mfma_f32_16x16x32_f16 v[86:89], v[214:217], v[182:185], v[86:89]
	v_mfma_f32_16x16x32_f16 v[74:77], v[206:209], v[190:193], v[74:77]
	v_mfma_f32_16x16x32_f16 v[78:81], v[214:217], v[190:193], v[78:81]
	v_mfma_f32_16x16x32_f16 v[70:73], v[206:209], v[198:201], v[70:73]
	v_mfma_f32_16x16x32_f16 v[66:69], v[214:217], v[198:201], v[66:69]
	s_add_i32 s93, s93, 2
	s_add_u32 s44, s44, 0x100
	s_addc_u32 s45, s45, 0
	s_add_u32 s91, s91, 0x100
	s_addc_u32 s92, s92, 0
	s_cmp_gt_u32 s93, 13
	s_barrier
	s_cbranch_scc1 .LBB0_264
	s_cmp_eq_u32 s93, 12
	s_cselect_b64 s[46:47], -1, 0
	s_and_b64 s[94:95], s[6:7], s[46:47]
	s_andn2_b64 vcc, exec, s[94:95]
	s_cbranch_vccnz .Lgb_body
	s_branch .Lgb_hdr_rest
.LBB0_264:
	s_and_b64 vcc, exec, s[6:7]
	s_cbranch_vccz .Lpl_skip8
	s_add_u32 s94, s43, 0x40080
	s_addc_u32 s95, s29, 0
	s_mov_b32 m0, s79
	v_lshl_add_u64 v[130:131], s[94:95], 0, v[160:161]
	global_load_lds_dwordx4 v[130:131], off
	v_lshl_add_u64 v[130:131], v[130:131], 0, s[0:1]
	s_mov_b32 m0, s80
	s_nop 0
	global_load_lds_dwordx4 v[130:131], off
